# gdn_prep QK^T/KK^T stage hand-scheduled: LDS operands issued up front with counted waits, branch-free masks
# speedup vs baseline: 1.0343x; 1.0082x over previous
; DI float bflo(unsigned u) { return __uint_as_float(u << 16); }
; DI void gdn_prep_unit(const Params& P, int h, int n, unsigned char* lds, int tid, u32x4 (&raw)[12], float& sbv, float& sav, int unext, bool cw_lds = false) {
;     ...
;         for (int j = 0; j < 4; ++j) { const u32x4 rw = raw[xx * 4 + j];
;             const float* wp = cw_lds ? (const float*)(lds + 86016) + (j * 3 + xx) * 64 + 8 * c8 : convw + j * 1536 + xx * 512 + h * 64 + 8 * c8;
;             const f32x4 w0 = *(const f32x4*)wp, w1 = *(const f32x4*)(wp + 4);
;             acc[0] += w0.x * bflo(rw.x); acc[1] += w0.y * bfhi(rw.x); acc[2] += w0.z * bflo(rw.y); acc[3] += w0.w * bfhi(rw.y);
;             acc[4] += w1.x * bflo(rw.z); acc[5] += w1.y * bfhi(rw.z); acc[6] += w1.z * bflo(rw.w); acc[7] += w1.w * bfhi(rw.w); }
; #pragma unroll
;         for (int e = 0; e < 8; ++e) y[xx][e] = acc[e] * sigmf(acc[e]);
;     }
;     const float sb_c = sbv, sa_c = sav;
;     float ssq = 0.f, ssk = 0.f;
; #pragma unroll
;     for (int e = 0; e < 8; ++e) { ssq += y[0][e] * y[0][e]; ssk += y[1][e] * y[1][e]; }
;     ssq += dpp_xor1(ssq); ssq += dpp_xor2(ssq); ssq += dpp_half_mirror(ssq);
;     ssk += dpp_xor1(ssk); ssk += dpp_xor2(ssk); ssk += dpp_half_mirror(ssk);
;     const float rq = rsqrtf(ssq + EPS) * 0.125f, rk = rsqrtf(ssk + EPS);
;     const float beta = sigmf(sb_c);
;     const float gt = -__expf(P.in[5][h]) * softplusf(sa_c + P.in[6][h]);
;     graw[t] = gt; bet[t] = beta;
;     PREP_BAR();
;     if (wave == 0) gcs[lane] = wave_incl_scan(graw[lane]);
;     PREP_BAR();
;     const float gc = gcs[t];
;     const float eg = __expf(gc);
;     { u32x4 kk, qq; float q[8], k[8];
; #pragma unroll
;       for (int e = 0; e < 8; ++e) { q[e] = y[0][e] * rq; k[e] = y[1][e] * rk; }
;       kk.x = pk2(k[0], k[1]); kk.y = pk2(k[2], k[3]); kk.z = pk2(k[4], k[5]); kk.w = pk2(k[6], k[7]);
;       qq.x = pk2(q[0], q[1]); qq.y = pk2(q[2], q[3]); qq.z = pk2(q[4], q[5]); qq.w = pk2(q[6], q[7]);
;       *(u32x4*)(Kimg + t * 72 + 8 * c8) = kk; *(u32x4*)(Qimg + t * 72 + 8 * c8) = qq;
; #pragma unroll
;       for (int e = 0; e < 8; e += 4) { const float kb = beta * eg;
;           *(f32x4*)(X + t * 132 + 8 * c8 + e) = (f32x4){y[2][e] * beta, y[2][e + 1] * beta, y[2][e + 2] * beta, y[2][e + 3] * beta};
;           *(f32x4*)(X + t * 132 + 64 + 8 * c8 + e) = (f32x4){k[e] * kb, k[e + 1] * kb, k[e + 2] * kb, k[e + 3] * kb}; }
.LBB0_494:
	s_or_b64 exec, exec, s[0:1]
	v_lshlrev_b32_e32 v222, 16, v34
	v_and_b32_e32 v223, 0xffff0000, v34
	s_waitcnt lgkmcnt(9)
	v_pk_fma_f32 v[80:81], v[80:81], v[222:223], 0 op_sel_hi:[1,1,0]
	v_lshlrev_b32_e32 v222, 16, v38
	v_and_b32_e32 v223, 0xffff0000, v38
	s_waitcnt lgkmcnt(7)
	v_pk_fma_f32 v[76:77], v[76:77], v[222:223], v[80:81]
	v_lshlrev_b32_e32 v80, 16, v44
	v_and_b32_e32 v81, 0xffff0000, v44
	s_waitcnt lgkmcnt(5)
	v_pk_fma_f32 v[72:73], v[72:73], v[80:81], v[76:77]
	v_lshlrev_b32_e32 v76, 16, v48
	v_and_b32_e32 v77, 0xffff0000, v48
	s_waitcnt lgkmcnt(3)
	v_pk_fma_f32 v[68:69], v[68:69], v[76:77], v[72:73]
	v_lshlrev_b32_e32 v72, 16, v35
	v_and_b32_e32 v73, 0xffff0000, v35
	v_pk_fma_f32 v[72:73], v[82:83], v[72:73], 0 op_sel_hi:[1,1,0]
	v_lshlrev_b32_e32 v76, 16, v39
	v_and_b32_e32 v77, 0xffff0000, v39
	v_pk_fma_f32 v[72:73], v[78:79], v[76:77], v[72:73]
	v_lshlrev_b32_e32 v76, 16, v45
	v_and_b32_e32 v77, 0xffff0000, v45
	v_pk_fma_f32 v[72:73], v[74:75], v[76:77], v[72:73]
	v_lshlrev_b32_e32 v74, 16, v49
	v_and_b32_e32 v75, 0xffff0000, v49
	v_pk_fma_f32 v[70:71], v[70:71], v[74:75], v[72:73]
	v_lshlrev_b32_e32 v72, 16, v36
	v_and_b32_e32 v73, 0xffff0000, v36
	v_pk_fma_f32 v[64:65], v[64:65], v[72:73], 0 op_sel_hi:[1,1,0]
	v_lshlrev_b32_e32 v72, 16, v40
	v_and_b32_e32 v73, 0xffff0000, v40
	v_pk_fma_f32 v[60:61], v[60:61], v[72:73], v[64:65]
	v_lshlrev_b32_e32 v64, 16, v46
	v_and_b32_e32 v65, 0xffff0000, v46
	v_pk_fma_f32 v[56:57], v[56:57], v[64:65], v[60:61]
	v_lshlrev_b32_e32 v60, 16, v50
	v_and_b32_e32 v61, 0xffff0000, v50
	s_waitcnt lgkmcnt(2)
	v_pk_fma_f32 v[60:61], v[52:53], v[60:61], v[56:57]
	v_lshlrev_b32_e32 v52, 16, v37
	v_and_b32_e32 v53, 0xffff0000, v37
	v_pk_fma_f32 v[52:53], v[66:67], v[52:53], 0 op_sel_hi:[1,1,0]
	v_lshlrev_b32_e32 v56, 16, v41
	v_and_b32_e32 v57, 0xffff0000, v41
	v_pk_fma_f32 v[52:53], v[62:63], v[56:57], v[52:53]
	v_lshlrev_b32_e32 v56, 16, v47
	v_and_b32_e32 v57, 0xffff0000, v47
	v_pk_fma_f32 v[52:53], v[58:59], v[56:57], v[52:53]
	v_mul_f32_e32 v56, 0xbfb8aa3b, v68
	v_exp_f32_e32 v58, v56
	v_lshlrev_b32_e32 v56, 16, v51
	v_and_b32_e32 v57, 0xffff0000, v51
	v_pk_fma_f32 v[62:63], v[54:55], v[56:57], v[52:53]
	v_mul_f32_e32 v53, 0xbfb8aa3b, v69
	v_exp_f32_e32 v53, v53
	v_add_f32_e32 v52, 1.0, v58
	v_mul_f32_e32 v54, 0xbfb8aa3b, v70
	v_exp_f32_e32 v54, v54
	v_rcp_f32_e32 v64, v52
	v_add_f32_e32 v52, 1.0, v53
	v_mul_f32_e32 v53, 0xbfb8aa3b, v71
	v_exp_f32_e32 v53, v53
	v_rcp_f32_e32 v65, v52
	v_add_f32_e32 v52, 1.0, v54
	v_mul_f32_e32 v54, 0xbfb8aa3b, v60
	v_exp_f32_e32 v54, v54
	v_rcp_f32_e32 v66, v52
	v_add_f32_e32 v52, 1.0, v53
	v_mul_f32_e32 v53, 0xbfb8aa3b, v61
	v_exp_f32_e32 v53, v53
	v_rcp_f32_e32 v67, v52
	v_add_f32_e32 v52, 1.0, v54
	v_mul_f32_e32 v54, 0xbfb8aa3b, v62
	v_rcp_f32_e32 v72, v52
	v_add_f32_e32 v52, 1.0, v53
	v_exp_f32_e32 v54, v54
	v_rcp_f32_e32 v73, v52
	v_mul_f32_e32 v52, 0xbfb8aa3b, v63
	v_exp_f32_e32 v55, v52
	v_pk_add_f32 v[52:53], v[118:119], v[120:121]
	s_mov_b32 s0, 0x358637bd
	v_pk_add_f32 v[52:53], v[52:53], s[0:1] op_sel_hi:[1,0]
	v_add_f32_e32 v54, 1.0, v54
	v_mul_f32_e32 v56, 0x4b800000, v53
	v_cmp_gt_f32_e32 vcc, s58, v53
	v_rcp_f32_e32 v74, v54
	v_add_f32_e32 v54, 1.0, v55
	v_cndmask_b32_e32 v53, v53, v56, vcc
	v_mul_f32_e32 v55, 0x4b800000, v52
	v_cmp_gt_f32_e64 s[0:1], s58, v52
	v_rsq_f32_e32 v53, v53
	s_waitcnt lgkmcnt(0)
	s_barrier
	ds_read_b32 v56, v136
	v_cndmask_b32_e64 v52, v52, v55, s[0:1]
	v_rsq_f32_e32 v55, v52
	v_rcp_f32_e32 v75, v54
	v_mul_f32_e32 v54, 0x45800000, v53
	v_cndmask_b32_e32 v52, v53, v54, vcc
	v_mul_f32_e32 v53, 0x45800000, v55
	v_mul_f32_e32 v52, 0x3e000000, v52
	v_cndmask_b32_e64 v54, v55, v53, s[0:1]
	s_waitcnt lgkmcnt(0)
	v_mul_f32_e32 v53, 0x3fb8aa3b, v56
	v_pk_mul_f32 v[76:77], v[100:101], v[52:53] op_sel_hi:[1,0]
	v_pk_mul_f32 v[100:101], v[104:105], v[52:53] op_sel_hi:[1,0]
	v_pk_mul_f32 v[104:105], v[106:107], v[52:53] op_sel_hi:[1,0]
	v_pk_mul_f32 v[106:107], v[108:109], v[54:55] op_sel_hi:[1,0]
	v_exp_f32_e32 v108, v53
	v_pk_mul_f32 v[78:79], v[114:115], v[54:55] op_sel_hi:[1,0]
	v_pk_mul_f32 v[80:81], v[102:103], v[52:53] op_sel_hi:[1,0]
	v_pk_mul_f32 v[82:83], v[112:113], v[54:55] op_sel_hi:[1,0]
	v_pk_mul_f32 v[102:103], v[110:111], v[54:55] op_sel_hi:[1,0]
	v_cvt_pk_bf16_f32 v52, v78, v79
	v_cvt_pk_bf16_f32 v53, v82, v83
	v_cvt_pk_bf16_f32 v54, v102, v103
	v_cvt_pk_bf16_f32 v55, v106, v107
	v_cvt_pk_bf16_f32 v56, v76, v77
	v_cvt_pk_bf16_f32 v57, v80, v81
	v_cvt_pk_bf16_f32 v58, v100, v101
	v_cvt_pk_bf16_f32 v59, v104, v105
	ds_write_b128 v137, v[52:55]
	ds_write_b128 v137, v[56:59] offset:9216
	v_pk_mul_f32 v[52:53], v[68:69], v[64:65]
	v_pk_mul_f32 v[54:55], v[70:71], v[66:67]
	v_mul_f32_e32 v56, v116, v108
	v_pk_mul_f32 v[54:55], v[116:117], v[54:55] op_sel_hi:[0,1]
	v_pk_mul_f32 v[52:53], v[116:117], v[52:53] op_sel_hi:[0,1]
	ds_write_b128 v138, v[52:55] offset:35840
	v_pk_mul_f32 v[54:55], v[82:83], v[56:57] op_sel_hi:[1,0]
	v_pk_mul_f32 v[52:53], v[78:79], v[56:57] op_sel_hi:[1,0]
	ds_write_b128 v138, v[52:55] offset:36096
	v_pk_mul_f32 v[52:53], v[60:61], v[72:73]
	v_pk_mul_f32 v[54:55], v[62:63], v[74:75]
	v_pk_mul_f32 v[52:53], v[116:117], v[52:53] op_sel_hi:[0,1]
	v_pk_mul_f32 v[54:55], v[116:117], v[54:55] op_sel_hi:[0,1]
	ds_write_b128 v138, v[52:55] offset:35856
	v_pk_mul_f32 v[54:55], v[106:107], v[56:57] op_sel_hi:[1,0]
	v_pk_mul_f32 v[52:53], v[102:103], v[56:57] op_sel_hi:[1,0]
	ds_write_b128 v138, v[52:55] offset:36112
	v_pk_mul_f32 v[52:53], v[76:77], v[108:109] op_sel_hi:[1,0]
	v_pk_mul_f32 v[54:55], v[80:81], v[108:109] op_sel_hi:[1,0]
	v_cvt_pk_bf16_f32 v52, v52, v53
	v_cvt_pk_bf16_f32 v53, v54, v55
	v_pk_mul_f32 v[54:55], v[100:101], v[108:109] op_sel_hi:[1,0]
	v_pk_mul_f32 v[56:57], v[104:105], v[108:109] op_sel_hi:[1,0]
	v_cvt_pk_bf16_f32 v54, v54, v55
	v_cvt_pk_bf16_f32 v55, v56, v57
	v_lshl_add_u64 v[56:57], v[88:89], 0, s[96:97]
	global_store_dwordx2 v[56:57], v[52:53], off
	v_lshl_add_u64 v[52:53], v[90:91], 0, s[96:97]
	global_store_dwordx2 v[52:53], v[54:55], off
	s_waitcnt lgkmcnt(0)
	s_barrier
; DI unsigned pk2(float lo, float hi) { f32x2_t v = {lo, hi}; bf16x2_t b = __builtin_convertvector(v, bf16x2_t); return __builtin_bit_cast(unsigned, b); }
; #define MFMA16(a, b, c) __builtin_amdgcn_mfma_f32_16x16x32_bf16((a), (b), (c), 0, 0, 0)
; #define PREP_BAR() do { asm volatile("s_waitcnt lgkmcnt(0)\n\ts_barrier" ::: "memory"); } while (0)
; DI void gdn_prep_unit(const Params& P, int h, int n, unsigned char* lds, int tid, u32x4 (&raw)[12], float& sbv, float& sav, int unext, bool cw_lds = false) {
;     ...
;     { const int l15 = lane & 15, g = lane >> 4;
; #pragma unroll
;       for (int bb = 0; bb < 2; ++bb) { const int blk = 2 * wave + bb, bi = blk >> 2, bj = blk & 3;
;           f32x4 aq = {0.f, 0.f, 0.f, 0.f}, ak = {0.f, 0.f, 0.f, 0.f};
; #pragma unroll
;           for (int s = 0; s < 2; ++s) {
;               const bf16x8 bk = *(const bf16x8*)(Kimg + (16 * bj + l15) * 72 + 32 * s + 8 * g);
;               const bf16x8 aqf = *(const bf16x8*)(Qimg + (16 * bi + l15) * 72 + 32 * s + 8 * g);
;               aq = MFMA16(aqf, bk, aq);
;               if (bj <= bi) { const bf16x8 akf = *(const bf16x8*)(Kimg + (16 * bi + l15) * 72 + 32 * s + 8 * g); ak = MFMA16(akf, bk, ak); }
;           }
;           const int j = 16 * bj + l15; const float gj = gcs[j]; const int pj = permpos(j);
; #pragma unroll
;           for (int r = 0; r < 4; ++r) { const int i = 16 * bi + 4 * g + r; const float dec = (j <= i) ? __expf(gcs[i] - gj) : 0.f;
;               Aimg[i * 64 + ((((pj >> 3) ^ (i >> 1)) & 7) << 3) + (pj & 7)] = (bf16_t)(pk2(aq[r] * dec, 0.f) & 0xffffu);
;               if (bj <= bi) Ml[i * 68 + j] = (j < i) ? bet[i] * ak[r] * dec : 0.f; }
;       } }
;     PREP_BAR();
;     if (unext >= 0) gdn_load(P, unext, tid, raw, sbv, sav);
	ds_read_b128 v[2:5], v139 offset:9216
	ds_read_b128 v[10:13], v218
	ds_read_b128 v[18:21], v219
	ds_read_b128 v[6:9], v139 offset:9280
	ds_read_b128 v[14:17], v218 offset:64
	ds_read_b128 v[22:25], v219 offset:64
	ds_read_b128 v[26:29], v139
	ds_read_b128 v[30:33], v139 offset:64
	ds_read_b128 v[34:37], v142
	ds_read_b128 v[52:55], v144
	ds_read_b32 v56, v140
	ds_read_b32 v57, v155
	v_add_u32_e32 v58, v141, v145
	s_waitcnt lgkmcnt(9)
	v_mfma_f32_16x16x32_bf16 v[60:63], v[2:5], v[10:13], 0
	v_mfma_f32_16x16x32_bf16 v[64:67], v[2:5], v[18:21], 0
	s_waitcnt lgkmcnt(6)
	v_mfma_f32_16x16x32_bf16 v[60:63], v[6:9], v[14:17], v[60:63]
	v_mfma_f32_16x16x32_bf16 v[64:67], v[6:9], v[22:25], v[64:67]
	s_waitcnt lgkmcnt(4)
	v_mfma_f32_16x16x32_bf16 v[240:243], v[26:29], v[10:13], 0
	v_mfma_f32_16x16x32_bf16 v[244:247], v[26:29], v[18:21], 0
	v_mfma_f32_16x16x32_bf16 v[240:243], v[30:33], v[14:17], v[240:243]
	v_mfma_f32_16x16x32_bf16 v[244:247], v[30:33], v[22:25], v[244:247]
	s_waitcnt lgkmcnt(0)
	v_sub_f32_e32 v248, v34, v56
	v_sub_f32_e32 v249, v35, v56
	v_sub_f32_e32 v250, v36, v56
	v_sub_f32_e32 v251, v37, v56
	v_sub_f32_e32 v252, v34, v57
	v_sub_f32_e32 v253, v35, v57
	v_sub_f32_e32 v254, v36, v57
	v_sub_f32_e32 v255, v37, v57
	v_mul_f32_e32 v248, 0x3fb8aa3b, v248
	v_mul_f32_e32 v249, 0x3fb8aa3b, v249
	v_mul_f32_e32 v250, 0x3fb8aa3b, v250
	v_mul_f32_e32 v251, 0x3fb8aa3b, v251
	v_mul_f32_e32 v252, 0x3fb8aa3b, v252
	v_mul_f32_e32 v253, 0x3fb8aa3b, v253
	v_mul_f32_e32 v254, 0x3fb8aa3b, v254
	v_mul_f32_e32 v255, 0x3fb8aa3b, v255
	v_exp_f32_e32 v248, v248
	v_exp_f32_e32 v249, v249
	v_exp_f32_e32 v250, v250
	v_exp_f32_e32 v251, v251
	v_exp_f32_e32 v252, v252
	v_exp_f32_e32 v253, v253
	v_exp_f32_e32 v254, v254
	v_exp_f32_e32 v255, v255
	s_nop 0
	v_cndmask_b32_e64 v248, 0, v248, s[12:13]
	v_cndmask_b32_e64 v249, 0, v249, s[16:17]
	v_cndmask_b32_e64 v250, 0, v250, s[18:19]
	v_cndmask_b32_e64 v251, 0, v251, s[22:23]
	v_cndmask_b32_e64 v252, 0, v252, s[28:29]
	v_cndmask_b32_e64 v253, 0, v253, s[34:35]
	v_cndmask_b32_e64 v254, 0, v254, s[36:37]
	v_cndmask_b32_e64 v255, 0, v255, s[40:41]
	v_mul_f32_e32 v60, v60, v248
	v_mul_f32_e32 v61, v61, v249
	v_mul_f32_e32 v62, v62, v250
	v_mul_f32_e32 v63, v63, v251
	v_mul_f32_e32 v64, v64, v252
	v_mul_f32_e32 v65, v65, v253
	v_mul_f32_e32 v66, v66, v254
	v_mul_f32_e32 v67, v67, v255
	v_cvt_pk_bf16_f32 v60, v60, v60
	v_cvt_pk_bf16_f32 v61, v61, v61
	v_cvt_pk_bf16_f32 v62, v62, v62
	v_cvt_pk_bf16_f32 v63, v63, v63
	v_cvt_pk_bf16_f32 v64, v64, v64
	v_cvt_pk_bf16_f32 v65, v65, v65
	v_cvt_pk_bf16_f32 v66, v66, v66
	v_cvt_pk_bf16_f32 v67, v67, v67
	ds_write_b16 v143, v60
	ds_write_b16 v147, v61
	ds_write_b16 v150, v62
	ds_write_b16 v153, v63
	ds_write_b16 v143, v64 offset:8
	ds_write_b16 v147, v65 offset:8
	ds_write_b16 v150, v66 offset:8
	ds_write_b16 v153, v67 offset:8
	s_and_b64 vcc, exec, s[10:11]
	s_cbranch_vccz .Ls4_noml0
	v_mul_f32_e32 v240, v240, v52
	v_mul_f32_e32 v241, v241, v53
	v_mul_f32_e32 v242, v242, v54
	v_mul_f32_e32 v243, v243, v55
	v_mul_f32_e32 v240, v248, v240
	v_mul_f32_e32 v241, v249, v241
	v_mul_f32_e32 v242, v250, v242
	v_mul_f32_e32 v243, v251, v243
	v_cndmask_b32_e64 v240, 0, v240, s[14:15]
	v_cndmask_b32_e64 v241, 0, v241, s[12:13]
	v_cndmask_b32_e64 v242, 0, v242, s[20:21]
	v_cndmask_b32_e64 v243, 0, v243, s[24:25]
	ds_write_b32 v58, v240 offset:18432
	ds_write_b32 v58, v241 offset:18704
	ds_write_b32 v58, v242 offset:18976
	ds_write_b32 v58, v243 offset:19248
.Ls4_noml0:
	s_and_b64 vcc, exec, s[26:27]
	s_cbranch_vccz .Ls4_noml1
	v_mul_f32_e32 v244, v244, v52
	v_mul_f32_e32 v245, v245, v53
	v_mul_f32_e32 v246, v246, v54
	v_mul_f32_e32 v247, v247, v55
	v_mul_f32_e32 v244, v252, v244
	v_mul_f32_e32 v245, v253, v245
	v_mul_f32_e32 v246, v254, v246
	v_mul_f32_e32 v247, v255, v247
	v_cndmask_b32_e64 v244, 0, v244, s[30:31]
	v_cndmask_b32_e64 v245, 0, v245, s[28:29]
	v_cndmask_b32_e64 v246, 0, v246, s[38:39]
	v_cndmask_b32_e64 v247, 0, v247, s[42:43]
	ds_write_b32 v58, v244 offset:18496
	ds_write_b32 v58, v245 offset:18768
	ds_write_b32 v58, v246 offset:19040
	ds_write_b32 v58, v247 offset:19312
.Ls4_noml1:
	s_cmp_lg_u32 s96, 0x38000
	s_waitcnt lgkmcnt(0)
	s_barrier
	s_cselect_b32 s0, s3, -1
	s_cmp_lt_i32 s0, 0
	s_cbranch_scc1 .LBB0_570
	s_and_b32 s2, s0, 7
	s_lshl_b32 s0, s0, 3
	s_and_b32 s0, s0, 0x7fffffc0
	v_mov_b32_e32 v4, v42
	v_mov_b32_e32 v5, v42
	v_add_u32_e32 v48, s0, v196
	s_lshl_b32 s0, s2, 7
	s_mov_b32 s1, s68
	v_mov_b32_e32 v2, v42
	v_mov_b32_e32 v3, v42
	v_mov_b64_e32 v[8:9], v[4:5]
	v_add_u32_e32 v38, -3, v48
	v_lshl_add_u64 v[34:35], v[84:85], 0, s[0:1]
	v_cmp_lt_u32_e32 vcc, 2, v48
	v_mov_b64_e32 v[6:7], v[2:3]
	s_and_saveexec_b64 s[0:1], vcc
	s_cbranch_execz .LBB0_553
	v_mov_b32_e32 v39, v42
	v_lshlrev_b64 v[6:7], 10, v[38:39]
	v_lshl_add_u64 v[6:7], v[34:35], 0, v[6:7]
	global_load_dwordx4 v[6:9], v[6:7], off
